# v45 plus P1 epilogue f32 K/V stores widened: permlane16/32 swaps make each dwordx4 store write 64 contiguous bytes per row instead of a 16-B checkerboard
# baseline (speedup 1.0000x reference)
.LBB0_106:
	s_lshl_b32 s10, s10, 8
	s_and_b32 s10, s10, 0x700
	s_mul_hi_i32 s21, s11, 0x2100000
	s_mul_i32 s11, s11, 0x2100000
	v_or_b32_e32 v150, s10, v158
	s_add_u32 s10, s47, s11
	s_addc_u32 s11, s48, s21
	v_lshlrev_b32_e32 v138, 1, v150
	v_lshl_add_u64 v[154:155], s[10:11], 0, v[138:139]
	v_lshlrev_b64 v[174:175], 12, v[152:153]
	s_cmp_lg_u64 s[30:31], 0
	v_lshlrev_b32_e32 v138, 2, v150
	v_lshl_add_u64 v[178:179], v[154:155], 0, v[174:175]
	v_cvt_pk_bf16_f32 v174, v126, v127
	v_cvt_pk_bf16_f32 v175, v128, v129
	v_cvt_pk_bf16_f32 v176, v122, v123
	v_cvt_pk_bf16_f32 v177, v124, v125
	s_cselect_b64 s[28:29], -1, 0
	s_cmp_eq_u64 s[30:31], 0
	v_lshl_add_u64 v[150:151], s[30:31], 0, v[138:139]
	global_store_dwordx4 v[178:179], v[174:177], off
	s_nop 1
	v_cvt_pk_bf16_f32 v174, v118, v119
	v_cvt_pk_bf16_f32 v175, v120, v121
	v_cvt_pk_bf16_f32 v176, v114, v115
	v_cvt_pk_bf16_f32 v177, v116, v117
	global_store_dwordx4 v[178:179], v[174:177], off offset:256
	s_cbranch_scc1 .LBB0_108
	s_nop 0
	v_lshlrev_b64 v[174:175], 13, v[152:153]
	v_lshl_add_u64 v[174:175], v[150:151], 0, v[174:175]
	v_and_b32_e32 v238, 48, v0
	v_sub_u32_e32 v174, v174, v238
	v_permlane16_swap_b32_e32 v126, v122
	v_permlane16_swap_b32_e32 v127, v123
	v_permlane16_swap_b32_e32 v128, v124
	v_permlane16_swap_b32_e32 v129, v125
	v_permlane16_swap_b32_e32 v118, v114
	v_permlane16_swap_b32_e32 v119, v115
	v_permlane16_swap_b32_e32 v120, v116
	v_permlane16_swap_b32_e32 v121, v117
	v_permlane32_swap_b32_e32 v126, v122
	v_permlane32_swap_b32_e32 v127, v123
	v_permlane32_swap_b32_e32 v128, v124
	v_permlane32_swap_b32_e32 v129, v125
	v_permlane32_swap_b32_e32 v118, v114
	v_permlane32_swap_b32_e32 v119, v115
	v_permlane32_swap_b32_e32 v120, v116
	v_permlane32_swap_b32_e32 v121, v117
	global_store_dwordx4 v[174:175], v[126:129], off
	global_store_dwordx4 v[174:175], v[122:125], off offset:64
	global_store_dwordx4 v[174:175], v[118:121], off offset:512
	global_store_dwordx4 v[174:175], v[114:117], off offset:576

.LBB0_110:
	v_lshlrev_b64 v[116:117], 12, v[114:115]
	v_lshl_add_u64 v[120:121], v[154:155], 0, v[116:117]
	v_cvt_pk_bf16_f32 v116, v110, v111
	v_cvt_pk_bf16_f32 v117, v112, v113
	v_cvt_pk_bf16_f32 v118, v106, v107
	v_cvt_pk_bf16_f32 v119, v108, v109
	v_cndmask_b32_e64 v122, 0, 1, s[28:29]
	global_store_dwordx4 v[120:121], v[116:119], off
	v_cmp_ne_u32_e64 s[10:11], 1, v122
	s_andn2_b64 vcc, exec, s[28:29]
	v_cvt_pk_bf16_f32 v116, v102, v103
	v_cvt_pk_bf16_f32 v117, v104, v105
	v_cvt_pk_bf16_f32 v118, v98, v99
	v_cvt_pk_bf16_f32 v119, v100, v101
	global_store_dwordx4 v[120:121], v[116:119], off offset:256
	s_cbranch_vccnz .LBB0_112
	v_lshlrev_b64 v[114:115], 13, v[114:115]
	v_lshl_add_u64 v[114:115], v[150:151], 0, v[114:115]
	v_and_b32_e32 v238, 48, v0
	v_sub_u32_e32 v114, v114, v238
	v_permlane16_swap_b32_e32 v110, v106
	v_permlane16_swap_b32_e32 v111, v107
	v_permlane16_swap_b32_e32 v112, v108
	v_permlane16_swap_b32_e32 v113, v109
	v_permlane16_swap_b32_e32 v102, v98
	v_permlane16_swap_b32_e32 v103, v99
	v_permlane16_swap_b32_e32 v104, v100
	v_permlane16_swap_b32_e32 v105, v101
	v_permlane32_swap_b32_e32 v110, v106
	v_permlane32_swap_b32_e32 v111, v107
	v_permlane32_swap_b32_e32 v112, v108
	v_permlane32_swap_b32_e32 v113, v109
	v_permlane32_swap_b32_e32 v102, v98
	v_permlane32_swap_b32_e32 v103, v99
	v_permlane32_swap_b32_e32 v104, v100
	v_permlane32_swap_b32_e32 v105, v101
	global_store_dwordx4 v[114:115], v[110:113], off
	global_store_dwordx4 v[114:115], v[106:109], off offset:64
	global_store_dwordx4 v[114:115], v[102:105], off offset:512
	global_store_dwordx4 v[114:115], v[98:101], off offset:576

.LBB0_114:
	v_lshlrev_b64 v[100:101], 12, v[98:99]
	v_lshl_add_u64 v[104:105], v[154:155], 0, v[100:101]
	v_cvt_pk_bf16_f32 v100, v94, v95
	v_cvt_pk_bf16_f32 v101, v96, v97
	v_cvt_pk_bf16_f32 v102, v90, v91
	v_cvt_pk_bf16_f32 v103, v92, v93
	global_store_dwordx4 v[104:105], v[100:103], off
	s_and_b64 vcc, exec, s[10:11]
	s_nop 0
	v_cvt_pk_bf16_f32 v100, v86, v87
	v_cvt_pk_bf16_f32 v101, v88, v89
	v_cvt_pk_bf16_f32 v102, v82, v83
	v_cvt_pk_bf16_f32 v103, v84, v85
	global_store_dwordx4 v[104:105], v[100:103], off offset:256
	s_cbranch_vccnz .LBB0_116
	v_lshlrev_b64 v[98:99], 13, v[98:99]
	v_lshl_add_u64 v[98:99], v[150:151], 0, v[98:99]
	v_and_b32_e32 v238, 48, v0
	v_sub_u32_e32 v98, v98, v238
	v_permlane16_swap_b32_e32 v94, v90
	v_permlane16_swap_b32_e32 v95, v91
	v_permlane16_swap_b32_e32 v96, v92
	v_permlane16_swap_b32_e32 v97, v93
	v_permlane16_swap_b32_e32 v86, v82
	v_permlane16_swap_b32_e32 v87, v83
	v_permlane16_swap_b32_e32 v88, v84
	v_permlane16_swap_b32_e32 v89, v85
	v_permlane32_swap_b32_e32 v94, v90
	v_permlane32_swap_b32_e32 v95, v91
	v_permlane32_swap_b32_e32 v96, v92
	v_permlane32_swap_b32_e32 v97, v93
	v_permlane32_swap_b32_e32 v86, v82
	v_permlane32_swap_b32_e32 v87, v83
	v_permlane32_swap_b32_e32 v88, v84
	v_permlane32_swap_b32_e32 v89, v85
	global_store_dwordx4 v[98:99], v[94:97], off
	global_store_dwordx4 v[98:99], v[90:93], off offset:64
	global_store_dwordx4 v[98:99], v[86:89], off offset:512
	global_store_dwordx4 v[98:99], v[82:85], off offset:576

.LBB0_118:
	v_lshlrev_b64 v[84:85], 12, v[82:83]
	v_lshl_add_u64 v[88:89], v[154:155], 0, v[84:85]
	v_cvt_pk_bf16_f32 v84, v78, v79
	v_cvt_pk_bf16_f32 v85, v80, v81
	v_cvt_pk_bf16_f32 v86, v74, v75
	v_cvt_pk_bf16_f32 v87, v76, v77
	global_store_dwordx4 v[88:89], v[84:87], off
	s_and_b64 vcc, exec, s[10:11]
	s_nop 0
	v_cvt_pk_bf16_f32 v84, v70, v71
	v_cvt_pk_bf16_f32 v85, v72, v73
	v_cvt_pk_bf16_f32 v86, v66, v67
	v_cvt_pk_bf16_f32 v87, v68, v69
	global_store_dwordx4 v[88:89], v[84:87], off offset:256
	s_cbranch_vccnz .LBB0_120
	v_lshlrev_b64 v[82:83], 13, v[82:83]
	v_lshl_add_u64 v[82:83], v[150:151], 0, v[82:83]
	v_and_b32_e32 v238, 48, v0
	v_sub_u32_e32 v82, v82, v238
	v_permlane16_swap_b32_e32 v78, v74
	v_permlane16_swap_b32_e32 v79, v75
	v_permlane16_swap_b32_e32 v80, v76
	v_permlane16_swap_b32_e32 v81, v77
	v_permlane16_swap_b32_e32 v70, v66
	v_permlane16_swap_b32_e32 v71, v67
	v_permlane16_swap_b32_e32 v72, v68
	v_permlane16_swap_b32_e32 v73, v69
	v_permlane32_swap_b32_e32 v78, v74
	v_permlane32_swap_b32_e32 v79, v75
	v_permlane32_swap_b32_e32 v80, v76
	v_permlane32_swap_b32_e32 v81, v77
	v_permlane32_swap_b32_e32 v70, v66
	v_permlane32_swap_b32_e32 v71, v67
	v_permlane32_swap_b32_e32 v72, v68
	v_permlane32_swap_b32_e32 v73, v69
	global_store_dwordx4 v[82:83], v[78:81], off
	global_store_dwordx4 v[82:83], v[74:77], off offset:64
	global_store_dwordx4 v[82:83], v[70:73], off offset:512
	global_store_dwordx4 v[82:83], v[66:69], off offset:576

.LBB0_122:
	v_lshlrev_b64 v[68:69], 12, v[66:67]
	v_lshl_add_u64 v[72:73], v[154:155], 0, v[68:69]
	v_cvt_pk_bf16_f32 v68, v62, v63
	v_cvt_pk_bf16_f32 v69, v64, v65
	v_cvt_pk_bf16_f32 v70, v58, v59
	v_cvt_pk_bf16_f32 v71, v60, v61
	global_store_dwordx4 v[72:73], v[68:71], off
	s_and_b64 vcc, exec, s[10:11]
	s_nop 0
	v_cvt_pk_bf16_f32 v68, v54, v55
	v_cvt_pk_bf16_f32 v69, v56, v57
	v_cvt_pk_bf16_f32 v70, v50, v51
	v_cvt_pk_bf16_f32 v71, v52, v53
	global_store_dwordx4 v[72:73], v[68:71], off offset:256
	s_cbranch_vccnz .LBB0_124
	v_lshlrev_b64 v[66:67], 13, v[66:67]
	v_lshl_add_u64 v[66:67], v[150:151], 0, v[66:67]
	v_and_b32_e32 v238, 48, v0
	v_sub_u32_e32 v66, v66, v238
	v_permlane16_swap_b32_e32 v62, v58
	v_permlane16_swap_b32_e32 v63, v59
	v_permlane16_swap_b32_e32 v64, v60
	v_permlane16_swap_b32_e32 v65, v61
	v_permlane16_swap_b32_e32 v54, v50
	v_permlane16_swap_b32_e32 v55, v51
	v_permlane16_swap_b32_e32 v56, v52
	v_permlane16_swap_b32_e32 v57, v53
	v_permlane32_swap_b32_e32 v62, v58
	v_permlane32_swap_b32_e32 v63, v59
	v_permlane32_swap_b32_e32 v64, v60
	v_permlane32_swap_b32_e32 v65, v61
	v_permlane32_swap_b32_e32 v54, v50
	v_permlane32_swap_b32_e32 v55, v51
	v_permlane32_swap_b32_e32 v56, v52
	v_permlane32_swap_b32_e32 v57, v53
	global_store_dwordx4 v[66:67], v[62:65], off
	global_store_dwordx4 v[66:67], v[58:61], off offset:64
	global_store_dwordx4 v[66:67], v[54:57], off offset:512
	global_store_dwordx4 v[66:67], v[50:53], off offset:576

.LBB0_126:
	v_lshlrev_b64 v[52:53], 12, v[50:51]
	v_lshl_add_u64 v[56:57], v[154:155], 0, v[52:53]
	v_cvt_pk_bf16_f32 v52, v46, v47
	v_cvt_pk_bf16_f32 v53, v48, v49
	v_cvt_pk_bf16_f32 v54, v42, v43
	v_cvt_pk_bf16_f32 v55, v44, v45
	global_store_dwordx4 v[56:57], v[52:55], off
	s_and_b64 vcc, exec, s[10:11]
	s_nop 0
	v_cvt_pk_bf16_f32 v52, v38, v39
	v_cvt_pk_bf16_f32 v53, v40, v41
	v_cvt_pk_bf16_f32 v54, v34, v35
	v_cvt_pk_bf16_f32 v55, v36, v37
	global_store_dwordx4 v[56:57], v[52:55], off offset:256
	s_cbranch_vccnz .LBB0_128
	v_lshlrev_b64 v[50:51], 13, v[50:51]
	v_lshl_add_u64 v[50:51], v[150:151], 0, v[50:51]
	v_and_b32_e32 v238, 48, v0
	v_sub_u32_e32 v50, v50, v238
	v_permlane16_swap_b32_e32 v46, v42
	v_permlane16_swap_b32_e32 v47, v43
	v_permlane16_swap_b32_e32 v48, v44
	v_permlane16_swap_b32_e32 v49, v45
	v_permlane16_swap_b32_e32 v38, v34
	v_permlane16_swap_b32_e32 v39, v35
	v_permlane16_swap_b32_e32 v40, v36
	v_permlane16_swap_b32_e32 v41, v37
	v_permlane32_swap_b32_e32 v46, v42
	v_permlane32_swap_b32_e32 v47, v43
	v_permlane32_swap_b32_e32 v48, v44
	v_permlane32_swap_b32_e32 v49, v45
	v_permlane32_swap_b32_e32 v38, v34
	v_permlane32_swap_b32_e32 v39, v35
	v_permlane32_swap_b32_e32 v40, v36
	v_permlane32_swap_b32_e32 v41, v37
	global_store_dwordx4 v[50:51], v[46:49], off
	global_store_dwordx4 v[50:51], v[42:45], off offset:64
	global_store_dwordx4 v[50:51], v[38:41], off offset:512
	global_store_dwordx4 v[50:51], v[34:37], off offset:576

.LBB0_130:
	v_lshlrev_b64 v[36:37], 12, v[34:35]
	v_lshl_add_u64 v[40:41], v[154:155], 0, v[36:37]
	v_cvt_pk_bf16_f32 v36, v30, v31
	v_cvt_pk_bf16_f32 v37, v32, v33
	v_cvt_pk_bf16_f32 v38, v26, v27
	v_cvt_pk_bf16_f32 v39, v28, v29
	global_store_dwordx4 v[40:41], v[36:39], off
	s_and_b64 vcc, exec, s[10:11]
	s_nop 0
	v_cvt_pk_bf16_f32 v36, v22, v23
	v_cvt_pk_bf16_f32 v37, v24, v25
	v_cvt_pk_bf16_f32 v38, v18, v19
	v_cvt_pk_bf16_f32 v39, v20, v21
	global_store_dwordx4 v[40:41], v[36:39], off offset:256
	s_cbranch_vccnz .LBB0_132
	v_lshlrev_b64 v[34:35], 13, v[34:35]
	v_lshl_add_u64 v[34:35], v[150:151], 0, v[34:35]
	v_and_b32_e32 v238, 48, v0
	v_sub_u32_e32 v34, v34, v238
	v_permlane16_swap_b32_e32 v30, v26
	v_permlane16_swap_b32_e32 v31, v27
	v_permlane16_swap_b32_e32 v32, v28
	v_permlane16_swap_b32_e32 v33, v29
	v_permlane16_swap_b32_e32 v22, v18
	v_permlane16_swap_b32_e32 v23, v19
	v_permlane16_swap_b32_e32 v24, v20
	v_permlane16_swap_b32_e32 v25, v21
	v_permlane32_swap_b32_e32 v30, v26
	v_permlane32_swap_b32_e32 v31, v27
	v_permlane32_swap_b32_e32 v32, v28
	v_permlane32_swap_b32_e32 v33, v29
	v_permlane32_swap_b32_e32 v22, v18
	v_permlane32_swap_b32_e32 v23, v19
	v_permlane32_swap_b32_e32 v24, v20
	v_permlane32_swap_b32_e32 v25, v21
	global_store_dwordx4 v[34:35], v[30:33], off
	global_store_dwordx4 v[34:35], v[26:29], off offset:64
	global_store_dwordx4 v[34:35], v[22:25], off offset:512
	global_store_dwordx4 v[34:35], v[18:21], off offset:576

.LBB0_134:
	v_lshlrev_b64 v[20:21], 12, v[18:19]
	v_lshl_add_u64 v[24:25], v[154:155], 0, v[20:21]
	v_cvt_pk_bf16_f32 v20, v14, v15
	v_cvt_pk_bf16_f32 v21, v16, v17
	v_cvt_pk_bf16_f32 v22, v10, v11
	v_cvt_pk_bf16_f32 v23, v12, v13
	global_store_dwordx4 v[24:25], v[20:23], off
	s_and_b64 vcc, exec, s[10:11]
	s_nop 0
	v_cvt_pk_bf16_f32 v20, v6, v7
	v_cvt_pk_bf16_f32 v21, v8, v9
	v_cvt_pk_bf16_f32 v22, v2, v3
	v_cvt_pk_bf16_f32 v23, v4, v5
	global_store_dwordx4 v[24:25], v[20:23], off offset:256
	s_cbranch_vccnz .LBB0_136
	v_lshlrev_b64 v[18:19], 13, v[18:19]
	v_lshl_add_u64 v[18:19], v[150:151], 0, v[18:19]
	v_and_b32_e32 v238, 48, v0
	v_sub_u32_e32 v18, v18, v238
	v_permlane16_swap_b32_e32 v14, v10
	v_permlane16_swap_b32_e32 v15, v11
	v_permlane16_swap_b32_e32 v16, v12
	v_permlane16_swap_b32_e32 v17, v13
	v_permlane16_swap_b32_e32 v6, v2
	v_permlane16_swap_b32_e32 v7, v3
	v_permlane16_swap_b32_e32 v8, v4
	v_permlane16_swap_b32_e32 v9, v5
	v_permlane32_swap_b32_e32 v14, v10
	v_permlane32_swap_b32_e32 v15, v11
	v_permlane32_swap_b32_e32 v16, v12
	v_permlane32_swap_b32_e32 v17, v13
	v_permlane32_swap_b32_e32 v6, v2
	v_permlane32_swap_b32_e32 v7, v3
	v_permlane32_swap_b32_e32 v8, v4
	v_permlane32_swap_b32_e32 v9, v5
	global_store_dwordx4 v[18:19], v[14:17], off
	global_store_dwordx4 v[18:19], v[10:13], off offset:64
	global_store_dwordx4 v[18:19], v[6:9], off offset:512
	global_store_dwordx4 v[18:19], v[2:5], off offset:576
